# convert non-W_in weights in the idle tail of in_proj (WGs>=64 have 3 tiles); W_in only in phase k=0
# speedup vs baseline: 1.0021x; 1.0021x over previous
.LBB0_6:
	s_lshr_b32 s93, s5, 6
	s_lshl_b32 s0, s92, 9
	s_mul_hi_i32 s2, s92, 0x55555556
	v_writelane_b32 v253, s0, 0
	s_add_u32 s0, s90, 0xc8
	s_addc_u32 s1, s91, 0
	v_writelane_b32 v253, s0, 1
	s_cmpk_lt_i32 s92, 0x100
	v_lshrrev_b32_e32 v2, 20, v0
	v_writelane_b32 v253, s1, 2
	s_cselect_b64 s[0:1], -1, 0
	v_writelane_b32 v253, s0, 3
	s_cmpk_gt_i32 s92, 0xbf
	v_lshrrev_b32_e32 v0, 10, v0
	v_writelane_b32 v253, s1, 4
	s_cselect_b64 s[0:1], -1, 0
	v_writelane_b32 v253, s0, 5
	s_lshr_b32 s3, s2, 31
	s_add_i32 s2, s2, s3
	v_writelane_b32 v253, s1, 6
	v_writelane_b32 v253, s2, 7
	s_mul_i32 s2, s2, 3
	s_sub_i32 s2, s92, s2
	s_add_i32 s1, s92, 0xc0
	v_writelane_b32 v253, s2, 8
	s_lshl_b32 s2, s92, 6
	s_cmpk_lt_i32 s2, 0x4000
	v_writelane_b32 v253, s2, 9
	s_cselect_b64 s[2:3], -1, 0
	v_writelane_b32 v253, s2, 10
	s_mul_i32 s0, s92, 3
	v_or_b32_e32 v0, v0, v2
	v_writelane_b32 v253, s3, 11
	s_lshl_b32 s2, s92, 3
	s_cmpk_gt_i32 s15, 0x3e8
	v_writelane_b32 v253, s2, 12
	s_cselect_b64 s[2:3], -1, 0
	v_writelane_b32 v253, s2, 13
	s_cmp_eq_u32 s4, 15
	s_mov_b32 s78, 0xc000
	v_writelane_b32 v253, s3, 14
	s_cselect_b64 s[2:3], -1, 0
	v_writelane_b32 v253, s2, 15
	s_cmp_eq_u32 s4, 14
	v_mov_b32_e32 v65, 0
	v_writelane_b32 v253, s3, 16
	s_cselect_b64 s[2:3], -1, 0
	v_writelane_b32 v253, s2, 17
	s_cmp_eq_u32 s4, 13
	v_mov_b32_e32 v188, 0x358637bd
	v_writelane_b32 v253, s3, 18
	s_cselect_b64 s[2:3], -1, 0
	v_writelane_b32 v253, s2, 19
	s_cmp_eq_u32 s4, 12
	s_mov_b32 s73, 0x800000
	v_writelane_b32 v253, s3, 20
	s_cselect_b64 s[2:3], -1, 0
	v_writelane_b32 v253, s2, 21
	s_cmp_eq_u32 s4, 11
	v_mov_b32_e32 v189, 0x3e91f4c4
	v_writelane_b32 v253, s3, 22
	s_cselect_b64 s[2:3], -1, 0
	v_writelane_b32 v253, s2, 23
	s_cmp_eq_u32 s4, 10
	v_mov_b32_e32 v250, 0x3c0881c4
	v_writelane_b32 v253, s3, 24
	s_cselect_b64 s[2:3], -1, 0
	v_writelane_b32 v253, s2, 25
	s_cmp_eq_u32 s4, 9
	v_mov_b32_e32 v251, 0xbab64f3b
	v_writelane_b32 v253, s3, 26
	s_cselect_b64 s[2:3], -1, 0
	v_writelane_b32 v253, s2, 27
	s_cmp_eq_u32 s4, 8
	v_mov_b32_e32 v202, 1
	v_writelane_b32 v253, s3, 28
	s_cselect_b64 s[2:3], -1, 0
	v_writelane_b32 v253, s2, 29
	s_cmp_eq_u32 s4, 7
	v_mov_b32_e32 v204, 0x41f00000
	v_writelane_b32 v253, s3, 30
	s_cselect_b64 s[2:3], -1, 0
	v_writelane_b32 v253, s2, 31
	s_cmp_eq_u32 s4, 6
	v_mov_b32_e32 v205, 0x30000
	v_writelane_b32 v253, s3, 32
	s_cselect_b64 s[2:3], -1, 0
	v_writelane_b32 v253, s2, 33
	s_cmp_eq_u32 s4, 5
	v_mov_b32_e32 v206, 0xf149f2ca
	v_writelane_b32 v253, s3, 34
	s_cselect_b64 s[2:3], -1, 0
	v_writelane_b32 v253, s2, 35
	s_cmp_eq_u32 s4, 4
	v_mov_b32_e32 v207, 0x6000
	v_writelane_b32 v253, s3, 36
	s_cselect_b64 s[2:3], -1, 0
	v_writelane_b32 v253, s2, 37
	s_cmp_eq_u32 s4, 3
	v_mov_b32_e32 v208, 0x461c4000
	v_writelane_b32 v253, s3, 38
	s_cselect_b64 s[2:3], -1, 0
	v_writelane_b32 v253, s2, 39
	s_cmp_eq_u32 s4, 2
	v_mov_b32_e32 v209, 0x37000000
	v_writelane_b32 v253, s3, 40
	s_cselect_b64 s[2:3], -1, 0
	v_writelane_b32 v253, s2, 41
	s_cmp_eq_u32 s4, 1
	v_mov_b32_e32 v210, 0x7f800000
	v_writelane_b32 v253, s3, 42
	s_cselect_b64 s[2:3], -1, 0
	v_writelane_b32 v253, s2, 43
	s_cmp_eq_u32 s4, 0
	v_not_b32_e32 v211, 63
	v_writelane_b32 v253, s3, 44
	s_cselect_b64 s[2:3], -1, 0
	v_writelane_b32 v253, s2, 45
	v_not_b32_e32 v212, 31
	v_mov_b32_e32 v213, 0x7fc00000
	v_writelane_b32 v253, s3, 46
	s_lshl_b32 s2, s4, 6
	s_cmp_lt_i32 s92, 64
	s_cselect_b32 s1, s1, -1
	v_writelane_b32 v253, s1, 47
	s_max_i32 s1, s92, 63
	s_sub_i32 s1, s1, 64
	v_writelane_b32 v253, s1, 48
	s_addk_i32 s0, 0xfdc0
	v_writelane_b32 v253, s0, 49
	s_lshl_b32 s0, s2, 2
	s_movk_i32 s3, 0x3ff
	v_writelane_b32 v253, s0, 50
	s_add_i32 s0, 0, 0x3c00
	v_and_or_b32 v0, v0, s3, v1
	v_writelane_b32 v253, s0, 51
	s_add_i32 s0, 0, 0x24004
	v_writelane_b32 v253, s0, 52
	v_cmp_eq_u32_e64 s[0:1], 0, v0
	s_mov_b32 s72, 0xc1f00000
	v_mbcnt_lo_u32_b32 v1, -1, 0
	v_writelane_b32 v253, s0, 53
	v_mbcnt_hi_u32_b32 v203, -1, v1
	s_movk_i32 s33, 0x600
	v_writelane_b32 v253, s1, 54
	v_writelane_b32 v253, s92, 55
	v_writelane_b32 v253, s90, 56
	s_movk_i32 s26, 0x7fff
	s_mov_b32 s97, 0x7e000
	v_writelane_b32 v253, s91, 57
	v_writelane_b32 v253, s86, 58
	s_movk_i32 s79, 0x204
	s_mov_b32 s27, 0x42b17218
	v_writelane_b32 v253, s87, 59
	s_mov_b32 s23, 0
	s_mov_b64 s[24:25], 0x80
	s_mov_b64 s[28:29], 0x100
	s_mov_b64 s[30:31], 0x1000
	s_mov_b64 s[34:35], 0x40080
	s_mov_b64 s[36:37], 0x30000
	s_mov_b64 s[20:21], 0xd260000
	s_mov_b64 s[38:39], 0xea00200
	s_mov_b64 s[18:19], 0xd278000
	s_mov_b64 s[44:45], 0xea00280
	v_writelane_b32 v253, s93, 60
	s_mov_b32 s98, 0
	v_writelane_b32 v255, s98, 63
	s_branch .LBB0_8

.LBB0_494:
	s_andn2_b64 vcc, exec, s[42:43]
	s_cbranch_vccnz .LBB0_602
	s_cmp_lg_u32 s71, 0
	s_mov_b32 s96, s88
	s_mov_b32 s22, s74
	s_mov_b32 s62, s75
	s_mov_b32 s63, s16
	s_cbranch_scc1 .LBB0_602
	v_readlane_b32 s2, v253, 1
	v_mov_b32_e32 v82, v203
	v_readlane_b32 s3, v253, 2
	s_load_dword s6, s[2:3], 0x0
	v_readlane_b32 s2, v253, 12
	s_add_i32 s7, s48, s2
	v_readlane_b32 s98, v255, 63
	s_cmp_eq_u32 s98, 0
	s_cbranch_scc1 .Lcw_regular
	s_add_i32 s98, s7, 0xfffffe00
	s_movk_i32 s99, 0x1530
	v_writelane_b32 v255, s99, 61
	s_movk_i32 s99, 0x650
	v_writelane_b32 v255, s99, 62
	s_branch .Lcw_init_done
.Lcw_regular:
	s_add_i32 s98, s7, 0x1000
	s_movk_i32 s99, 0x1650
	v_writelane_b32 v255, s99, 61
	s_mov_b32 s99, 0
	v_writelane_b32 v255, s99, 62
.Lcw_init_done:
	s_nop 1
	v_readlane_b32 s99, v255, 61
	s_cmp_ge_i32 s98, s99
	s_cbranch_scc1 .LBB0_587
	v_readlane_b32 s52, v253, 63
	s_waitcnt lgkmcnt(0)
	s_lshl_b32 s10, s6, 3
	v_readlane_b32 s99, v255, 63
	s_cmp_lg_u32 s99, 0
	s_cselect_b32 s10, 0x600, s10
	v_readlane_b32 s66, v254, 13
	v_readlane_b32 s2, v254, 43
	v_readlane_b32 s53, v254, 0
	v_readlane_b32 s54, v254, 1
	v_readlane_b32 s55, v254, 2
	v_readlane_b32 s56, v254, 3
	v_readlane_b32 s57, v254, 4
	v_readlane_b32 s58, v254, 5
	v_readlane_b32 s59, v254, 6
	v_readlane_b32 s60, v254, 7
	v_readlane_b32 s61, v254, 8
	v_readlane_b32 s62, v254, 9
	v_readlane_b32 s63, v254, 10
	v_readlane_b32 s64, v254, 11
	v_readlane_b32 s65, v254, 12
	v_readlane_b32 s67, v254, 14
	v_readlane_b32 s3, v254, 44
	s_add_u32 s22, s66, s2
	s_addc_u32 s51, s67, s3
	v_readlane_b32 s52, v254, 15
	v_readlane_b32 s62, v254, 25
	v_readlane_b32 s63, v254, 26
	v_readlane_b32 s53, v254, 16
	v_readlane_b32 s54, v254, 17
	v_readlane_b32 s55, v254, 18
	v_readlane_b32 s56, v254, 19
	v_readlane_b32 s57, v254, 20
	v_readlane_b32 s58, v254, 21
	v_readlane_b32 s59, v254, 22
	v_readlane_b32 s60, v254, 23
	v_readlane_b32 s61, v254, 24
	s_mov_b32 s96, s88
	s_mov_b32 vcc_lo, s74
	s_mov_b32 vcc_hi, s75
	s_mov_b64 s[74:75], s[90:91]
	s_mov_b64 s[30:31], s[86:87]
	s_mov_b64 s[90:91], s[62:63]
	v_readlane_b32 s64, v254, 27
	s_mov_b64 s[80:81], s[52:53]
	v_readlane_b32 s65, v254, 28
	s_add_u32 s64, s80, s2
	s_mov_b64 s[82:83], s[54:55]
	s_addc_u32 s65, s81, s3
	s_mov_b64 s[88:89], s[60:61]
	s_mov_b64 s[86:87], s[58:59]
	s_mov_b64 s[84:85], s[56:57]
	s_add_u32 s62, s82, s2
	s_addc_u32 s63, s83, s3
	s_add_u32 s60, s84, s2
	v_readlane_b32 s66, v254, 29
	v_readlane_b32 s67, v254, 30
	s_addc_u32 s61, s85, s3
	s_mov_b64 s[94:95], s[66:67]
	s_add_u32 s66, s86, s2
	s_addc_u32 s67, s87, s3
	s_add_u32 s58, s88, s2
	s_addc_u32 s59, s89, s3
	s_add_u32 s49, s90, s2
	s_addc_u32 s50, s91, s3
	s_add_u32 s68, s94, s2
	s_addc_u32 s69, s95, s3
	s_mov_b32 s11, s93
	s_mov_b32 s17, s92
	v_readlane_b32 s88, v254, 31
	v_readlane_b32 s89, v254, 32
	s_add_u32 s70, s88, s2
	v_readlane_b32 s90, v254, 33
	s_addc_u32 s71, s89, s3
	v_readlane_b32 s91, v254, 34
	s_add_u32 s76, s90, s2
	v_readlane_b32 s92, v254, 35
	s_addc_u32 s77, s91, s3
	v_readlane_b32 s93, v254, 36
	s_add_u32 s82, s92, s2
	v_readlane_b32 s94, v254, 37
	s_addc_u32 s83, s93, s3
	v_readlane_b32 s95, v254, 38
	s_add_u32 s86, s94, s2
	s_addc_u32 s87, s95, s3
	s_lshl_b32 s2, s48, 14
	s_add_i32 s88, s2, 0
	s_lshl_b64 s[42:43], s[46:47], 18
	s_mov_b32 s93, s11
	s_add_u32 s11, s8, 0x2390000
	s_mov_b64 s[90:91], s[46:47]
	s_mov_b32 s92, s17
	s_addc_u32 s17, s9, 0
	s_lshl_b32 s46, s90, 8
	s_mul_i32 s52, s90, 0x180
	s_ashr_i32 s47, s46, 31
	s_ashr_i32 s53, s52, 31
	s_lshl_b64 s[56:57], s[90:91], 19
	s_lshl_b64 s[54:55], s[90:91], 21
	s_lshl_b64 s[40:41], s[90:91], 22
	s_lshl_b64 s[2:3], s[90:91], 24
	s_add_u32 s49, s49, s42
	s_addc_u32 s50, s50, s43
	s_add_u32 s58, s58, s56
	s_addc_u32 s59, s59, s57
	s_lshl_b64 s[42:43], s[46:47], 2
	s_add_u32 s42, s60, s42
	s_addc_u32 s43, s61, s43
	s_cmp_lg_u64 s[84:85], 0
	s_cselect_b64 s[46:47], -1, 0
	s_add_u32 s60, s66, s56
	s_addc_u32 s61, s67, s57
	s_mul_i32 s56, s90, 0x120000
	s_add_u32 s62, s62, s56
	s_mul_hi_i32 s56, s90, 0x120000
	s_addc_u32 s63, s63, s56
	s_lshl_b64 s[52:53], s[52:53], 2
	v_and_b32_e32 v1, 7, v82
	s_add_u32 s56, s64, s52
	v_lshlrev_b32_e32 v64, 4, v1
	s_addc_u32 s57, s65, s53
	v_lshl_add_u64 v[4:5], s[8:9], 0, v[64:65]
	s_mov_b64 s[52:53], 0x2310000
	v_lshl_add_u64 v[40:41], v[4:5], 0, s[52:53]
	s_mov_b64 s[52:53], 0x2280000
	v_lshl_add_u64 v[42:43], v[4:5], 0, s[52:53]
	s_mov_b64 s[52:53], 0x2180000
	v_lshl_add_u64 v[44:45], v[4:5], 0, s[52:53]
	s_mov_b64 s[52:53], 0x2080000
	v_lshl_add_u64 v[46:47], v[4:5], 0, s[52:53]
	s_mov_b64 s[52:53], 0x1e80000
	v_lshl_add_u64 v[48:49], v[4:5], 0, s[52:53]
	s_mov_b64 s[52:53], 0x1680000
	v_lshl_add_u64 v[52:53], v[4:5], 0, s[52:53]
	s_mov_b64 s[52:53], 0xe80000
	s_cmp_lg_u64 s[80:81], 0
	v_lshl_add_u64 v[38:39], s[60:61], 0, v[64:65]
	v_lshl_add_u64 v[54:55], v[4:5], 0, s[52:53]
	s_cselect_b64 s[60:61], -1, 0
	s_add_u32 s52, s70, s54
	s_addc_u32 s53, s71, s55
	v_lshl_add_u64 v[58:59], s[52:53], 0, v[64:65]
	s_add_u32 s52, s68, s54
	s_addc_u32 s53, s69, s55
	s_add_u32 s40, s76, s40
	v_lshl_add_u64 v[36:37], s[58:59], 0, v[64:65]
	s_mul_i32 s59, s90, 0xca0000
	s_addc_u32 s41, s77, s41
	s_mul_hi_i32 s58, s90, 0xca0000
	v_lshl_add_u64 v[62:63], s[40:41], 0, v[64:65]
	s_add_u32 s40, s22, s59
	s_addc_u32 s41, s51, s58
	v_lshl_add_u64 v[66:67], s[40:41], 0, v[64:65]
	s_add_u32 s40, s86, s2
	s_addc_u32 s41, s87, s3
	s_add_u32 s2, s82, s2
	v_bfe_u32 v83, v82, 3, 3
	s_addc_u32 s3, s83, s3
	v_mul_u32_u24_e32 v0, 0x420, v1
	v_lshlrev_b32_e32 v2, 2, v83
	v_lshl_add_u64 v[70:71], s[2:3], 0, v[64:65]
	s_lshl_b32 s2, s7, 2
	v_add3_u32 v85, s88, v0, v2
	v_lshlrev_b32_e32 v0, 2, v1
	v_lshlrev_b32_e32 v2, 3, v1
	v_or_b32_e32 v1, 32, v83
	s_add_i32 s55, s2, 0x7fff9380
	s_lshl_b32 s2, s7, 1
	v_add_u32_e32 v84, s88, v64
	s_mov_b32 s88, s96
	s_mov_b64 s[90:91], s[74:75]
	s_mov_b32 s75, vcc_hi
	s_mov_b32 s74, vcc_lo
	v_mul_u32_u24_e32 v86, 0x84, v83
	v_or_b32_e32 v87, 8, v83
	v_or_b32_e32 v88, 16, v83
	v_or_b32_e32 v89, 24, v83
	v_mul_u32_u24_e32 v90, 0x84, v1
	v_lshl_add_u64 v[50:51], s[0:1], 0, v[64:65]
	v_lshl_add_u64 v[56:57], s[62:63], 0, v[64:65]
	v_lshl_add_u64 v[60:61], s[52:53], 0, v[64:65]
	s_mov_b64 s[86:87], s[30:31]
	s_mov_b64 s[30:31], 0x1000
	v_lshl_add_u64 v[68:69], s[40:41], 0, v[64:65]
	s_lshl_b32 s51, s7, 5
	s_lshl_b32 s52, s6, 8
	s_lshl_b32 s53, s7, 4
	s_lshl_b32 s54, s6, 7
	s_lshl_b32 s58, s6, 5
	s_add_i32 s59, s2, 0xffffcd60
	s_lshl_b32 s62, s6, 4
	v_lshlrev_b32_e32 v72, 2, v0
	v_lshlrev_b32_e32 v74, 1, v2
	s_branch .LBB0_499
.LBB0_498:
	s_add_i32 s98, s98, s10
	v_readlane_b32 s99, v255, 61
	s_cmp_ge_i32 s98, s99
	s_cbranch_scc1 .LBB0_587
.LBB0_499:
	v_readlane_b32 s99, v255, 62
	s_cmpk_gt_i32 s98, 0xfff
	s_cselect_b32 s99, s99, 0
	s_add_i32 s7, s98, s99
	s_lshl_b32 s51, s7, 5
	s_lshl_b32 s53, s7, 4
	s_lshl_b32 s55, s7, 2
	s_add_i32 s55, s55, 0x7fff9380
	s_lshl_b32 s59, s7, 1
	s_add_i32 s59, s59, 0xffffcd60
	s_cmpk_gt_i32 s7, 0x7ff
	s_mov_b64 s[2:3], -1
	s_cbranch_scc0 .LBB0_577
	s_cmpk_gt_u32 s7, 0xfff
	s_cbranch_scc0 .LBB0_574
	s_cmpk_gt_u32 s7, 0x164f
	s_cbranch_scc0 .LBB0_571
	s_cmpk_gt_u32 s7, 0x184f
	s_cbranch_scc0 .LBB0_568
	s_cmpk_gt_u32 s7, 0x194f
	s_cbranch_scc0 .LBB0_565
	s_cmpk_gt_u32 s7, 0x1a4f
	s_cbranch_scc0 .LBB0_562
	s_cmpk_gt_u32 s7, 0x1adf
	s_cbranch_scc0 .LBB0_547
	s_cmpk_gt_u32 s7, 0x1b1f
	s_cbranch_scc0 .LBB0_532
	s_cmpk_gt_u32 s7, 0x1b5f
	s_cbranch_scc0 .LBB0_509
	s_add_i32 s2, s7, 0xffffe4a0
	s_lshr_b32 s22, s2, 3
	s_lshl_b64 s[2:3], s[22:23], 16
	s_add_u32 s2, s49, s2
	s_addc_u32 s3, s50, s3
	s_and_b32 s41, s51, 0x60
	s_and_b32 s40, s53, 64
	s_lshl_b32 s63, s22, 7
	s_lshl_b32 s64, s41, 2
	s_add_u32 s2, s2, s64
	v_or_b32_e32 v2, s40, v83
	s_addc_u32 s3, s3, 0
	v_mov_b32_e32 v73, v65
	v_lshl_add_u64 v[0:1], s[2:3], 0, v[72:73]
	v_lshlrev_b32_e32 v64, 9, v2
	v_lshl_add_u64 v[28:29], v[0:1], 0, v[64:65]
	s_movk_i32 s2, 0x2000
	v_add_co_u32_e32 v8, vcc, s2, v28
	s_movk_i32 s2, 0x4000
	s_nop 0
	v_addc_co_u32_e32 v9, vcc, 0, v29, vcc
	v_add_co_u32_e32 v16, vcc, s2, v28
	s_movk_i32 s2, 0x6000
	s_nop 0
	v_addc_co_u32_e32 v17, vcc, 0, v29, vcc
	v_add_co_u32_e32 v24, vcc, s2, v28
	global_load_dwordx4 v[0:3], v[28:29], off nt
	s_nop 0
	v_addc_co_u32_e32 v25, vcc, 0, v29, vcc
	global_load_dwordx4 v[4:7], v[8:9], off offset:-4096 nt
	s_nop 0
	global_load_dwordx4 v[8:11], v[8:9], off nt
	s_nop 0
	global_load_dwordx4 v[12:15], v[16:17], off offset:-4096 nt
	s_nop 0
	global_load_dwordx4 v[16:19], v[16:17], off nt
	s_nop 0
	global_load_dwordx4 v[20:23], v[24:25], off offset:-4096 nt
	s_nop 0
	global_load_dwordx4 v[24:27], v[24:25], off nt
	s_movk_i32 s2, 0x7000
	v_add_co_u32_e32 v28, vcc, s2, v28
	v_add_u32_e32 v73, v84, v86
	s_nop 0
	v_addc_co_u32_e32 v29, vcc, 0, v29, vcc
	global_load_dwordx4 v[28:31], v[28:29], off nt
	v_add_u32_e32 v76, 0x420, v73
	v_add_u32_e32 v77, 0x428, v73
	v_add_u32_e32 v78, 0x840, v73
	v_add_u32_e32 v79, 0x848, v73
	v_add_u32_e32 v80, 0xc60, v73
	v_add_u32_e32 v81, 0xc68, v73
	v_add_u32_e32 v91, 0x1080, v73
	v_add_u32_e32 v92, 0x1088, v73
	v_add_u32_e32 v93, 0x14a0, v73
	v_add_u32_e32 v94, 0x14a8, v73
	v_add_u32_e32 v95, 0x18c0, v73
	v_add_u32_e32 v96, 0x18c8, v73
	v_add_u32_e32 v97, 0x1ce0, v73
	v_add_u32_e32 v98, 0x1ce8, v73
	s_or_b32 s41, s63, s41
	s_lshl_b32 s2, s22, 8
	s_add_u32 s2, s11, s2
	s_addc_u32 s3, s17, 0
	s_lshl_b32 s22, s40, 1
	s_add_u32 s2, s2, s22
	v_mov_b32_e32 v75, v65
	v_or_b32_e32 v64, s41, v83
	s_addc_u32 s3, s3, 0
	v_lshlrev_b64 v[32:33], 10, v[64:65]
	v_lshl_add_u64 v[34:35], s[2:3], 0, v[74:75]
	v_or_b32_e32 v64, s41, v87
	s_mov_b64 s[2:3], 0
	s_waitcnt vmcnt(0)
	ds_write2_b32 v73, v0, v1 offset1:1
	ds_write2_b32 v73, v2, v3 offset0:2 offset1:3
	ds_write2_b32 v76, v4, v5 offset1:1
	ds_write2_b32 v77, v6, v7 offset1:1
	ds_write2_b32 v78, v8, v9 offset1:1
	ds_write2_b32 v79, v10, v11 offset1:1
	ds_write2_b32 v80, v12, v13 offset1:1
	ds_write2_b32 v81, v14, v15 offset1:1
	ds_write2_b32 v91, v16, v17 offset1:1
	ds_write2_b32 v92, v18, v19 offset1:1
	ds_write2_b32 v93, v20, v21 offset1:1
	ds_write2_b32 v94, v22, v23 offset1:1
	ds_write2_b32 v95, v24, v25 offset1:1
	ds_write2_b32 v96, v26, v27 offset1:1
	ds_write2_b32 v97, v28, v29 offset1:1
	ds_write2_b32 v98, v30, v31 offset1:1
	s_waitcnt lgkmcnt(0)
	ds_read2_b32 v[4:5], v85 offset0:33 offset1:41
	ds_read2_b32 v[6:7], v85 offset1:8
	ds_read2_b32 v[8:9], v85 offset0:66 offset1:74
	ds_read2_b32 v[10:11], v85 offset0:99 offset1:107
	ds_read2_b32 v[12:13], v85 offset0:132 offset1:140
	ds_read2_b32 v[14:15], v85 offset0:165 offset1:173
	ds_read2_b32 v[16:17], v85 offset0:198 offset1:206
	ds_read2_b32 v[18:19], v85 offset0:231 offset1:239
	v_lshl_add_u64 v[20:21], v[34:35], 0, v[32:33]
	s_waitcnt lgkmcnt(6)
	v_cvt_pk_bf16_f32 v0, v6, v4
	s_waitcnt lgkmcnt(4)
	v_cvt_pk_bf16_f32 v1, v8, v10
	s_waitcnt lgkmcnt(2)
	v_cvt_pk_bf16_f32 v2, v12, v14
	s_waitcnt lgkmcnt(0)
	v_cvt_pk_bf16_f32 v3, v16, v18
	global_store_dwordx4 v[20:21], v[0:3], off
	v_cvt_pk_bf16_f32 v4, v7, v5
	v_cvt_pk_bf16_f32 v5, v9, v11
	v_cvt_pk_bf16_f32 v6, v13, v15
	v_cvt_pk_bf16_f32 v7, v17, v19
	ds_read2_b32 v[8:9], v85 offset0:49 offset1:57
	ds_read2_b32 v[10:11], v85 offset0:16 offset1:24
	ds_read2_b32 v[12:13], v85 offset0:82 offset1:90
	ds_read2_b32 v[14:15], v85 offset0:115 offset1:123
	ds_read2_b32 v[16:17], v85 offset0:148 offset1:156
	ds_read2_b32 v[18:19], v85 offset0:181 offset1:189
	ds_read2_b32 v[20:21], v85 offset0:214 offset1:222
	ds_read2_b32 v[22:23], v85 offset0:247 offset1:255
	v_lshlrev_b64 v[0:1], 10, v[64:65]
	v_lshl_add_u64 v[0:1], v[34:35], 0, v[0:1]
	v_or_b32_e32 v64, s41, v88
	global_store_dwordx4 v[0:1], v[4:7], off
	s_waitcnt lgkmcnt(6)
	v_cvt_pk_bf16_f32 v0, v10, v8
	s_waitcnt lgkmcnt(4)
	v_cvt_pk_bf16_f32 v1, v12, v14
	v_lshlrev_b64 v[4:5], 10, v[64:65]
	s_waitcnt lgkmcnt(2)
	v_cvt_pk_bf16_f32 v2, v16, v18
	s_waitcnt lgkmcnt(0)
	v_cvt_pk_bf16_f32 v3, v20, v22
	v_lshl_add_u64 v[4:5], v[34:35], 0, v[4:5]
	v_or_b32_e32 v64, s41, v89
	global_store_dwordx4 v[4:5], v[0:3], off
	v_lshlrev_b64 v[4:5], 10, v[64:65]
	v_lshl_add_u64 v[4:5], v[34:35], 0, v[4:5]
	v_cvt_pk_bf16_f32 v0, v11, v9
	v_cvt_pk_bf16_f32 v1, v13, v15
	v_cvt_pk_bf16_f32 v2, v17, v19
	v_cvt_pk_bf16_f32 v3, v21, v23
	global_store_dwordx4 v[4:5], v[0:3], off
	s_waitcnt lgkmcnt(0)

.LBB0_595:
	s_or_b64 exec, exec, s[40:41]
	s_add_i32 s2, s14, 7
	s_cmp_gt_u32 s2, 18
	s_cbranch_scc1 .LBB0_601
	v_readlane_b32 s2, v255, 63
	s_cmp_lg_u32 s2, 0
	s_cbranch_scc1 .LBB0_601
	s_lshl_b32 s2, s48, 3
	v_readlane_b32 s3, v253, 9
	s_add_i32 s2, s2, s3
	v_mov_b32_e32 v16, v203
	s_cmpk_gt_i32 s2, 0x3fff
	s_cbranch_scc1 .LBB0_601
	v_lshlrev_b32_e32 v0, 4, v16
	v_readlane_b32 s10, v254, 45
	v_and_b32_e32 v64, 0x3f0, v0
	v_readlane_b32 s11, v254, 46
	s_nop 4
	global_load_dwordx4 v[0:3], v64, s[10:11]
	global_load_dwordx4 v[4:7], v64, s[10:11] offset:1024
	global_load_dwordx4 v[8:11], v64, s[10:11] offset:2048
	global_load_dwordx4 v[12:15], v64, s[10:11] offset:3072
	v_and_b32_e32 v17, 64, v203
	v_add_u32_e32 v17, 64, v17
	v_xor_b32_e32 v18, 1, v203
	v_cmp_lt_i32_e32 vcc, v18, v17
	s_lshl_b32 s40, s6, 6
	v_readlane_b32 s6, v254, 41
	v_cndmask_b32_e32 v18, v203, v18, vcc
	v_lshlrev_b32_e32 v58, 2, v18
	v_xor_b32_e32 v18, 2, v203
	v_cmp_lt_i32_e32 vcc, v18, v17
	v_readlane_b32 s7, v254, 42
	s_ashr_i32 s3, s2, 31
	v_cndmask_b32_e32 v18, v203, v18, vcc
	v_lshlrev_b32_e32 v59, 2, v18
	v_xor_b32_e32 v18, 4, v203
	v_cmp_lt_i32_e32 vcc, v18, v17
	v_lshl_add_u64 v[32:33], s[6:7], 0, v[64:65]
	s_lshl_b64 s[6:7], s[2:3], 12
	v_cndmask_b32_e32 v18, v203, v18, vcc
	v_lshlrev_b32_e32 v60, 2, v18
	v_xor_b32_e32 v18, 8, v203
	v_cmp_lt_i32_e32 vcc, v18, v17
	v_readlane_b32 s52, v253, 63
	v_readlane_b32 s10, v254, 43
	v_cndmask_b32_e32 v18, v203, v18, vcc
	v_lshlrev_b32_e32 v61, 2, v18
	v_xor_b32_e32 v18, 16, v203
	v_cmp_lt_i32_e32 vcc, v18, v17
	v_readlane_b32 s53, v254, 0
	v_readlane_b32 s11, v254, 44
	v_cndmask_b32_e32 v18, v203, v18, vcc
	v_lshlrev_b32_e32 v62, 2, v18
	v_xor_b32_e32 v18, 32, v203
	s_add_u32 s10, s52, s10
	v_cmp_lt_i32_e32 vcc, v18, v17
	s_addc_u32 s11, s53, s11
	s_add_u32 s6, s10, s6
	v_cndmask_b32_e32 v17, v203, v18, vcc
	v_and_b32_e32 v18, 63, v16
	v_lshlrev_b32_e32 v64, 4, v18
	s_addc_u32 s7, s11, s7
	v_lshlrev_b32_e32 v63, 2, v17
	v_lshl_add_u64 v[16:17], s[6:7], 0, v[64:65]
	s_mov_b64 s[6:7], 0x800
	s_ashr_i32 s41, s40, 31
	v_lshl_add_u64 v[36:37], v[16:17], 0, s[6:7]
	s_lshl_b64 s[10:11], s[40:41], 12
	s_lshl_b64 s[6:7], s[2:3], 11
	s_add_u32 s3, s4, s6
	s_addc_u32 s7, s5, s7
	v_readlane_b32 s42, v254, 39
	v_readlane_b32 s43, v254, 40
	s_add_u32 s6, s42, s3
	v_lshlrev_b32_e32 v64, 3, v18
	s_addc_u32 s7, s43, s7
	v_lshl_add_u64 v[16:17], s[6:7], 0, v[64:65]
	s_mov_b64 s[6:7], 0xba00400
	v_lshl_add_u64 v[34:35], v[32:33], 0, s[30:31]
	v_lshl_add_u64 v[38:39], v[16:17], 0, s[6:7]
	s_lshl_b64 s[42:43], s[40:41], 11
	v_readlane_b32 s54, v254, 1
	v_readlane_b32 s55, v254, 2
	v_readlane_b32 s56, v254, 3
	v_readlane_b32 s57, v254, 4
	v_readlane_b32 s58, v254, 5
	v_readlane_b32 s59, v254, 6
	v_readlane_b32 s60, v254, 7
	v_readlane_b32 s61, v254, 8
	v_readlane_b32 s62, v254, 9
	v_readlane_b32 s63, v254, 10
	v_readlane_b32 s64, v254, 11
	v_readlane_b32 s65, v254, 12
	v_readlane_b32 s66, v254, 13
	v_readlane_b32 s67, v254, 14

.LBB0_621:
	s_add_i32 s17, s14, 1
	v_readlane_b32 s98, v255, 63
	s_cmp_eq_u32 s98, 0
	s_cbranch_scc1 .Lrp_chk_start
	s_mov_b32 s98, 0
	v_writelane_b32 v255, s98, 63
	s_add_i32 s14, s14, 1
	s_add_i32 s17, s14, 1
	s_branch .Lrp_done
.Lrp_chk_start:
	s_cmp_eq_u32 s14, 3
	s_cselect_b32 s98, 1, 0
	s_cmp_eq_u32 s14, 13
	s_cselect_b32 s98, 1, s98
	v_readlane_b32 s99, v253, 55
	s_cmp_gt_u32 s99, 63
	s_cselect_b32 s98, s98, 0
	s_cmp_eq_u32 s98, 0
	s_cbranch_scc1 .Lrp_done
	v_writelane_b32 v255, s98, 63
	s_add_i32 s17, s14, -1
	s_branch .LBB0_681
.Lrp_done:
	s_cmp_ge_i32 s17, s15
	s_cbranch_scc1 .LBB0_681
	v_readlane_b32 s2, v253, 13
	v_readlane_b32 s3, v253, 14
	s_andn2_b64 vcc, exec, s[2:3]
	s_cbranch_vccnz .LBB0_634
	s_waitcnt vmcnt(0)
	s_barrier
	s_mov_b64 s[2:3], exec
	v_readlane_b32 s4, v253, 53
	v_readlane_b32 s5, v253, 54
	s_and_b64 s[4:5], s[2:3], s[4:5]
	s_mov_b64 exec, s[4:5]
	s_cbranch_execz .LBB0_633
	v_readlane_b32 s4, v253, 1
	v_readlane_b32 s5, v253, 2
	buffer_wbl2 sc1
	s_load_dwordx2 s[4:5], s[4:5], 0x58
	s_mov_b64 s[6:7], exec
	v_mbcnt_lo_u32_b32 v1, s6, 0
	v_mbcnt_hi_u32_b32 v1, s7, v1
	v_cmp_eq_u32_e32 vcc, 0, v1
	s_waitcnt lgkmcnt(0)
	global_load_dword v0, v65, s[4:5] offset:40
	s_and_saveexec_b64 s[8:9], vcc
	s_cbranch_execz .LBB0_626
	s_bcnt1_i32_b64 s6, s[6:7]
	v_mov_b32_e32 v2, s6
	global_atomic_add v2, v65, v2, s[4:5] offset:32 sc0
